# adds: GLA scan issues one L2-warming load per lane for chunk c+2 after chunk c+1's loads (counted waits +1)
# speedup vs baseline: 1.0089x; 1.0011x over previous
.LBB0_1315:
	s_lshl_b32 s10, s53, 2
	s_ashr_i32 s11, s53, 6
	s_and_b32 s10, s10, 28
	s_and_b32 s62, s11, 3
	s_add_i32 s31, s10, s11
	s_and_b32 s10, s53, 32
	s_bfe_i32 s63, s53, 0x10005
	s_lshl_b32 s84, s62, 8
	s_cmp_eq_u32 s10, 0
	s_cselect_b64 s[70:71], -1, 0
	s_and_b64 s[10:11], s[70:71], exec
	s_movk_i32 s11, 0xc00
	s_cselect_b32 s56, s11, 0x1000
	v_readlane_b32 s11, v253, 40
	v_readlane_b32 s57, v252, 53
	s_cselect_b32 s11, s57, s11
	v_readlane_b32 s57, v253, 39
	s_cselect_b32 s10, 1, -1
	s_cselect_b32 s74, s96, s57
	s_add_u32 s56, s34, s56
	s_addc_u32 s57, s35, 0
	s_add_u32 s56, s56, s84
	s_addc_u32 s57, s57, 0
	s_lshl_b32 s75, s62, 9
	v_readlane_b32 s62, v253, 49
	s_add_u32 s62, s62, s75
	v_readlane_b32 s64, v253, 50
	s_addc_u32 s65, s64, 0
	s_lshl_b32 s72, s53, 4
	s_and_b32 s77, s72, 0x180
	s_add_u32 s72, s62, s77
	s_addc_u32 s73, s65, 0
	s_ashr_i32 s65, s31, 2
	v_lshl_add_u64 v[46:47], v[30:31], 1, s[56:57]
	s_lshl_b32 s56, s65, 8
	s_add_i32 s56, s56, 0x10000
	s_and_b32 s31, s63, 0xff
	s_or_b32 s76, s56, s31
	s_waitcnt vmcnt(0)
	v_mov_b32_e32 v20, s76
	v_mad_i32_i24 v110, s10, v52, s10
	v_mad_i32_i24 v2, s10, v52, v20
	v_add_u32_e32 v111, s10, v110
	v_ashrrev_i32_e32 v3, 31, v2
	v_add_u32_e32 v8, s76, v110
	v_add_u32_e32 v14, s76, v111
	v_lshlrev_b64 v[2:3], 13, v[2:3]
	v_ashrrev_i32_e32 v9, 31, v8
	v_ashrrev_i32_e32 v15, 31, v14
	v_add_u32_e32 v112, s10, v111
	v_lshl_add_u64 v[42:43], v[34:35], 0, s[84:85]
	v_lshl_add_u64 v[44:45], v[36:37], 0, s[84:85]
	v_lshl_add_u64 v[4:5], v[46:47], 0, v[2:3]
	v_lshlrev_b64 v[8:9], 13, v[8:9]
	v_lshlrev_b64 v[14:15], 13, v[14:15]
	v_add_u32_e32 v113, s10, v112
	v_lshl_add_u64 v[6:7], v[44:45], 0, v[2:3]
	v_lshl_add_u64 v[2:3], v[42:43], 0, v[2:3]
	v_lshl_add_u64 v[10:11], v[46:47], 0, v[8:9]
	v_lshl_add_u64 v[12:13], v[44:45], 0, v[8:9]
	v_lshl_add_u64 v[8:9], v[42:43], 0, v[8:9]
	v_lshl_add_u64 v[16:17], v[46:47], 0, v[14:15]
	v_lshl_add_u64 v[18:19], v[44:45], 0, v[14:15]
	global_load_dword v115, v[4:5], off
	global_load_dword v116, v[6:7], off
	global_load_dword v118, v[2:3], off
	global_load_dword v119, v[10:11], off
	global_load_dword v121, v[12:13], off
	global_load_dword v122, v[8:9], off
	global_load_dword v124, v[16:17], off
	global_load_dword v127, v[18:19], off
	v_add_u32_e32 v4, s76, v112
	v_add_u32_e32 v114, s10, v113
	v_ashrrev_i32_e32 v5, 31, v4
	v_add_u32_e32 v10, s76, v113
	v_add_u32_e32 v16, s76, v114
	v_lshlrev_b64 v[4:5], 13, v[4:5]
	v_ashrrev_i32_e32 v11, 31, v10
	v_ashrrev_i32_e32 v17, 31, v16
	v_lshl_add_u64 v[2:3], v[42:43], 0, v[14:15]
	v_lshl_add_u64 v[6:7], v[46:47], 0, v[4:5]
	v_lshlrev_b64 v[10:11], 13, v[10:11]
	v_lshlrev_b64 v[16:17], 13, v[16:17]
	v_add_u32_e32 v117, s10, v114
	v_lshl_add_u64 v[8:9], v[44:45], 0, v[4:5]
	v_lshl_add_u64 v[4:5], v[42:43], 0, v[4:5]
	v_lshl_add_u64 v[12:13], v[46:47], 0, v[10:11]
	v_lshl_add_u64 v[14:15], v[44:45], 0, v[10:11]
	v_lshl_add_u64 v[10:11], v[42:43], 0, v[10:11]
	v_lshl_add_u64 v[18:19], v[46:47], 0, v[16:17]
	global_load_dword v130, v[2:3], off
	global_load_dword v132, v[6:7], off
	global_load_dword v133, v[8:9], off
	global_load_dword v135, v[4:5], off
	global_load_dword v136, v[12:13], off
	global_load_dword v137, v[14:15], off
	global_load_dword v138, v[10:11], off
	global_load_dword v143, v[18:19], off
	v_add_u32_e32 v6, s76, v117
	v_add_u32_e32 v120, s10, v117
	v_ashrrev_i32_e32 v7, 31, v6
	v_add_u32_e32 v12, s76, v120
	v_lshlrev_b64 v[6:7], 13, v[6:7]
	v_ashrrev_i32_e32 v13, 31, v12
	v_add_u32_e32 v123, s10, v120
	v_lshl_add_u64 v[2:3], v[44:45], 0, v[16:17]
	v_lshl_add_u64 v[8:9], v[46:47], 0, v[6:7]
	v_lshlrev_b64 v[12:13], 13, v[12:13]
	v_add_u32_e32 v125, s10, v123
	v_lshl_add_u64 v[4:5], v[42:43], 0, v[16:17]
	v_lshl_add_u64 v[10:11], v[44:45], 0, v[6:7]
	v_lshl_add_u64 v[6:7], v[42:43], 0, v[6:7]
	v_lshl_add_u64 v[14:15], v[46:47], 0, v[12:13]
	v_lshl_add_u64 v[16:17], v[44:45], 0, v[12:13]
	v_lshl_add_u64 v[12:13], v[42:43], 0, v[12:13]
	global_load_dword v144, v[2:3], off
	global_load_dword v145, v[4:5], off
	global_load_dword v146, v[8:9], off
	global_load_dword v147, v[10:11], off
	global_load_dword v148, v[6:7], off
	global_load_dword v149, v[14:15], off
	global_load_dword v150, v[16:17], off
	global_load_dword v151, v[12:13], off
	v_add_u32_e32 v2, s76, v123
	v_add_u32_e32 v8, s76, v125
	v_add_u32_e32 v126, s10, v125
	v_ashrrev_i32_e32 v3, 31, v2
	v_ashrrev_i32_e32 v9, 31, v8
	v_add_u32_e32 v14, s76, v126
	v_lshlrev_b64 v[2:3], 13, v[2:3]
	v_lshlrev_b64 v[8:9], 13, v[8:9]
	v_ashrrev_i32_e32 v15, 31, v14
	v_add_u32_e32 v128, s10, v126
	v_lshl_add_u64 v[4:5], v[46:47], 0, v[2:3]
	v_lshl_add_u64 v[10:11], v[46:47], 0, v[8:9]
	v_lshlrev_b64 v[14:15], 13, v[14:15]
	v_add_u32_e32 v129, s10, v128
	v_lshl_add_u64 v[6:7], v[44:45], 0, v[2:3]
	v_lshl_add_u64 v[2:3], v[42:43], 0, v[2:3]
	v_lshl_add_u64 v[12:13], v[44:45], 0, v[8:9]
	v_lshl_add_u64 v[8:9], v[42:43], 0, v[8:9]
	v_lshl_add_u64 v[16:17], v[46:47], 0, v[14:15]
	v_lshl_add_u64 v[18:19], v[44:45], 0, v[14:15]
	global_load_dword v152, v[4:5], off
	global_load_dword v153, v[6:7], off
	global_load_dword v154, v[2:3], off
	global_load_dword v155, v[10:11], off
	global_load_dword v156, v[12:13], off
	global_load_dword v157, v[8:9], off
	global_load_dword v158, v[16:17], off
	global_load_dword v159, v[18:19], off
	v_add_u32_e32 v4, s76, v128
	v_add_u32_e32 v10, s76, v129
	v_add_u32_e32 v131, s10, v129
	v_ashrrev_i32_e32 v5, 31, v4
	v_ashrrev_i32_e32 v11, 31, v10
	v_add_u32_e32 v16, s76, v131
	v_lshlrev_b64 v[4:5], 13, v[4:5]
	v_lshlrev_b64 v[10:11], 13, v[10:11]
	v_ashrrev_i32_e32 v17, 31, v16
	v_lshl_add_u64 v[2:3], v[42:43], 0, v[14:15]
	v_lshl_add_u64 v[6:7], v[46:47], 0, v[4:5]
	v_lshl_add_u64 v[12:13], v[46:47], 0, v[10:11]
	v_lshlrev_b64 v[16:17], 13, v[16:17]
	v_add_u32_e32 v134, s10, v131
	v_lshl_add_u64 v[8:9], v[44:45], 0, v[4:5]
	v_lshl_add_u64 v[4:5], v[42:43], 0, v[4:5]
	v_lshl_add_u64 v[14:15], v[44:45], 0, v[10:11]
	v_lshl_add_u64 v[10:11], v[42:43], 0, v[10:11]
	v_lshl_add_u64 v[18:19], v[46:47], 0, v[16:17]
	global_load_dword v160, v[2:3], off
	global_load_dword v161, v[6:7], off
	global_load_dword v162, v[8:9], off
	global_load_dword v163, v[4:5], off
	global_load_dword v164, v[12:13], off
	global_load_dword v165, v[14:15], off
	global_load_dword v166, v[10:11], off
	global_load_dword v167, v[18:19], off
	v_add_u32_e32 v6, s76, v134
	v_mad_i32_i24 v12, s10, v63, v20
	v_ashrrev_i32_e32 v7, 31, v6
	v_ashrrev_i32_e32 v13, 31, v12
	v_lshl_add_u64 v[2:3], v[44:45], 0, v[16:17]
	v_lshlrev_b64 v[6:7], 13, v[6:7]
	v_lshlrev_b64 v[12:13], 13, v[12:13]
	v_lshl_add_u64 v[4:5], v[42:43], 0, v[16:17]
	v_lshl_add_u64 v[8:9], v[46:47], 0, v[6:7]
	v_lshl_add_u64 v[10:11], v[44:45], 0, v[6:7]
	v_lshl_add_u64 v[6:7], v[42:43], 0, v[6:7]
	v_lshl_add_u64 v[14:15], v[46:47], 0, v[12:13]
	v_lshl_add_u64 v[16:17], v[44:45], 0, v[12:13]
	v_lshl_add_u64 v[12:13], v[42:43], 0, v[12:13]
	global_load_dword v168, v[2:3], off
	global_load_dword v169, v[4:5], off
	global_load_dword v170, v[8:9], off
	global_load_dword v171, v[10:11], off
	global_load_dword v172, v[6:7], off
	global_load_dword v173, v[14:15], off
	global_load_dword v174, v[16:17], off
	global_load_dword v175, v[12:13], off
	v_mad_i32_i24 v2, s10, v33, v20
	v_ashrrev_i32_e32 v3, 31, v2
	v_lshl_add_u64 v[48:49], v[38:39], 1, s[72:73]
	v_lshlrev_b64 v[2:3], 13, v[2:3]
	v_lshl_add_u64 v[2:3], v[48:49], 0, v[2:3]
	global_load_dwordx4 v[18:21], v[2:3], off
	global_load_dword v201, v[2:3], off
	s_lshl_b32 s65, s65, 13
	s_add_u32 s31, s74, s75
	s_addc_u32 s11, s11, 0
	s_add_u32 s31, s31, s77
	s_addc_u32 s11, s11, 0
	s_add_u32 s62, s31, s52
	s_addc_u32 s63, s11, 0
	v_mov_b32_e32 v41, v0
	v_mov_b32_e32 v2, 0
	s_mov_b32 s57, 0
	v_mul_i32_i24_e32 v139, s10, v52
	v_mul_i32_i24_e32 v140, s10, v63
	v_mul_i32_i24_e32 v141, s10, v33
	v_lshl_add_u64 v[50:51], s[62:63], 0, v[40:41]
	v_mul_lo_u32 v41, s10, v91
	v_mul_lo_u32 v142, s10, v96
	s_movk_i32 s74, 0xff40
	s_movk_i32 s75, 0x20bf
	v_mov_b32_e32 v3, v2
	v_mov_b32_e32 v4, v2
	v_mov_b32_e32 v5, v2
	v_mov_b32_e32 v14, v2
	v_mov_b32_e32 v15, v2
	v_mov_b32_e32 v16, v2
	v_mov_b32_e32 v17, v2
	v_mov_b32_e32 v6, v2
	v_mov_b32_e32 v7, v2
	v_mov_b32_e32 v8, v2
	v_mov_b32_e32 v9, v2
	v_mov_b32_e32 v10, v2
	v_mov_b32_e32 v11, v2
	v_mov_b32_e32 v12, v2
	v_mov_b32_e32 v13, v2
	s_branch .LBB0_1317

.LBB0_1317:
	s_waitcnt vmcnt(49)
	v_perm_b32 v26, v115, v115, v32
	v_add_f32_e32 v176, 0, v26
	s_waitcnt vmcnt(46)
	v_perm_b32 v26, v119, v119, v32
	v_add_f32_e32 v177, v176, v26
	s_waitcnt vmcnt(43)
	v_perm_b32 v26, v124, v124, v32
	v_add_f32_e32 v178, v177, v26
	s_waitcnt vmcnt(40)
	v_perm_b32 v26, v132, v132, v32
	v_add_f32_e32 v179, v178, v26
	s_waitcnt vmcnt(37)
	v_perm_b32 v26, v136, v136, v32
	v_add_f32_e32 v180, v179, v26
	s_waitcnt vmcnt(34)
	v_perm_b32 v26, v143, v143, v32
	v_add_f32_e32 v181, v180, v26
	s_waitcnt vmcnt(31)
	v_perm_b32 v26, v146, v146, v32
	v_add_f32_e32 v182, v181, v26
	s_waitcnt vmcnt(28)
	v_perm_b32 v26, v149, v149, v32
	v_add_f32_e32 v183, v182, v26
	s_waitcnt vmcnt(25)
	v_perm_b32 v26, v152, v152, v32
	v_add_f32_e32 v184, v183, v26
	s_waitcnt vmcnt(22)
	v_perm_b32 v26, v155, v155, v32
	v_add_f32_e32 v185, v184, v26
	s_waitcnt vmcnt(19)
	v_perm_b32 v26, v158, v158, v32
	v_add_f32_e32 v186, v185, v26
	s_waitcnt vmcnt(16)
	v_perm_b32 v26, v161, v161, v32
	v_add_f32_e32 v187, v186, v26
	s_waitcnt vmcnt(13)
	v_perm_b32 v26, v164, v164, v32
	v_add_f32_e32 v188, v187, v26
	s_waitcnt vmcnt(10)
	v_perm_b32 v26, v167, v167, v32
	v_add_f32_e32 v189, v188, v26
	s_waitcnt vmcnt(7)
	v_perm_b32 v26, v170, v170, v32
	v_add_f32_e32 v190, v189, v26
	s_waitcnt vmcnt(4)
	v_perm_b32 v26, v173, v173, v32
	v_add_f32_e32 v191, v190, v26
	ds_bpermute_b32 v26, v53, v191
	ds_bpermute_b32 v28, v54, v191
	ds_bpermute_b32 v27, v55, v191
	ds_bpermute_b32 v29, v56, v191
	v_cvt_pk_bf16_f32 v22, v2, v3
	v_cvt_pk_bf16_f32 v23, v4, v5
	v_cvt_pk_bf16_f32 v24, v14, v15
	v_cvt_pk_bf16_f32 v25, v16, v17
	s_waitcnt lgkmcnt(0)
	s_barrier
	ds_write2_b64 v103, v[22:23], v[24:25] offset1:4
	v_cvt_pk_bf16_f32 v22, v6, v7
	v_cvt_pk_bf16_f32 v23, v8, v9
	v_cvt_pk_bf16_f32 v24, v10, v11
	v_cvt_pk_bf16_f32 v25, v12, v13
	ds_write2_b64 v103, v[22:23], v[24:25] offset0:8 offset1:12
	v_cndmask_b32_e64 v22, v26, 0, s[0:1]
	v_cndmask_b32_e64 v23, 0, v28, s[2:3]
	v_add_f32_e32 v22, v22, v23
	v_cndmask_b32_e64 v23, 0, v27, s[4:5]
	v_add_f32_e32 v192, v22, v23
	v_pk_add_f32 v[22:23], v[26:27], v[28:29]
	v_add_f32_e32 v22, v22, v23
	v_add_f32_e32 v23, v176, v192
	v_exp_f32_e32 v25, v23
	v_perm_b32 v24, v116, v116, v32
	v_exp_f32_e64 v26, -v23
	v_exp_f32_e32 v22, v22
	v_mul_f32_e32 v23, v25, v24
	v_cvt_pk_bf16_f32 v23, v23, s0
	ds_write_b16 v64, v23
	v_add_f32_e32 v23, v177, v192
	v_exp_f32_e32 v24, v23
	v_exp_f32_e64 v27, -v23
	v_perm_b32 v25, v121, v121, v32
	v_perm_b32 v29, v122, v122, v1
	v_perm_b32 v28, v118, v118, v32
	v_mul_f32_e32 v23, v24, v25
	v_mul_f32_e32 v24, v26, v28
	v_cvt_pk_bf16_f32 v23, v23, s0
	v_cvt_pk_bf16_f32 v24, v24, s0
	ds_write_b16 v64, v24 offset:17408
	v_pk_mul_f32 v[24:25], v[22:23], v[26:27] op_sel_hi:[0,1]
	ds_write_b16 v65, v23
	v_mul_f32_e32 v23, v27, v29
	v_cvt_pk_bf16_f32 v23, v23, s0
	ds_write_b16 v65, v23 offset:17408
	v_add_f32_e32 v23, v178, v192
	v_pk_mul_f32 v[24:25], v[24:25], v[28:29]
	v_exp_f32_e32 v28, v23
	v_perm_b32 v27, v127, v127, v32
	v_exp_f32_e64 v26, -v23
	v_mul_f32_e32 v23, v28, v27
	v_cvt_pk_bf16_f32 v23, v23, s0
	ds_write_b16 v66, v23
	v_add_f32_e32 v23, v179, v192
	v_exp_f32_e32 v28, v23
	v_perm_b32 v177, v133, v133, v32
	v_exp_f32_e64 v27, -v23
	v_mul_f32_e32 v23, v28, v177
	v_perm_b32 v28, v130, v130, v32
	v_mul_f32_e32 v176, v26, v28
	v_cvt_pk_bf16_f32 v23, v23, s0
	v_perm_b32 v29, v135, v135, v1
	v_cvt_pk_bf16_f32 v176, v176, s0
	ds_write_b16 v66, v176 offset:17408
	v_pk_mul_f32 v[176:177], v[22:23], v[26:27] op_sel_hi:[0,1]
	ds_write_b16 v67, v23
	v_mul_f32_e32 v23, v27, v29
	v_cvt_pk_bf16_f32 v23, v23, s0
	ds_write_b16 v67, v23 offset:17408
	v_add_f32_e32 v23, v180, v192
	v_pk_mul_f32 v[176:177], v[176:177], v[28:29]
	v_exp_f32_e32 v28, v23
	v_perm_b32 v27, v137, v137, v32
	v_exp_f32_e64 v26, -v23
	v_mul_f32_e32 v23, v28, v27
	v_cvt_pk_bf16_f32 v23, v23, s0
	ds_write_b16 v68, v23
	v_add_f32_e32 v23, v181, v192
	v_exp_f32_e32 v28, v23
	v_perm_b32 v179, v144, v144, v32
	v_exp_f32_e64 v27, -v23
	v_mul_f32_e32 v23, v28, v179
	v_perm_b32 v28, v138, v138, v32
	v_mul_f32_e32 v178, v26, v28
	v_cvt_pk_bf16_f32 v23, v23, s0
	v_perm_b32 v29, v145, v145, v1
	v_cvt_pk_bf16_f32 v178, v178, s0
	ds_write_b16 v68, v178 offset:17408
	v_pk_mul_f32 v[178:179], v[22:23], v[26:27] op_sel_hi:[0,1]
	ds_write_b16 v69, v23
	v_mul_f32_e32 v23, v27, v29
	v_cvt_pk_bf16_f32 v23, v23, s0
	ds_write_b16 v69, v23 offset:17408
	v_add_f32_e32 v23, v182, v192
	v_pk_mul_f32 v[178:179], v[178:179], v[28:29]
	v_exp_f32_e32 v28, v23
	v_perm_b32 v27, v147, v147, v32
	v_exp_f32_e64 v26, -v23
	v_mul_f32_e32 v23, v28, v27
	v_cvt_pk_bf16_f32 v23, v23, s0
	ds_write_b16 v70, v23
	v_add_f32_e32 v23, v183, v192
	v_exp_f32_e32 v28, v23
	v_perm_b32 v181, v150, v150, v32
	v_exp_f32_e64 v27, -v23
	v_mul_f32_e32 v23, v28, v181
	v_perm_b32 v28, v148, v148, v32
	v_mul_f32_e32 v180, v26, v28
	v_cvt_pk_bf16_f32 v23, v23, s0
	v_perm_b32 v29, v151, v151, v1
	v_cvt_pk_bf16_f32 v180, v180, s0
	ds_write_b16 v70, v180 offset:17408
	v_pk_mul_f32 v[180:181], v[22:23], v[26:27] op_sel_hi:[0,1]
	ds_write_b16 v71, v23
	v_mul_f32_e32 v23, v27, v29
	v_cvt_pk_bf16_f32 v23, v23, s0
	ds_write_b16 v71, v23 offset:17408
	v_add_f32_e32 v23, v184, v192
	v_pk_mul_f32 v[180:181], v[180:181], v[28:29]
	v_exp_f32_e32 v28, v23
	v_perm_b32 v27, v153, v153, v32
	v_exp_f32_e64 v26, -v23
	v_mul_f32_e32 v23, v28, v27
	v_cvt_pk_bf16_f32 v23, v23, s0
	ds_write_b16 v72, v23
	v_add_f32_e32 v23, v185, v192
	v_exp_f32_e32 v28, v23
	v_perm_b32 v183, v156, v156, v32
	v_exp_f32_e64 v27, -v23
	v_mul_f32_e32 v23, v28, v183
	v_perm_b32 v28, v154, v154, v32
	v_mul_f32_e32 v182, v26, v28
	v_cvt_pk_bf16_f32 v23, v23, s0
	v_perm_b32 v29, v157, v157, v1
	v_cvt_pk_bf16_f32 v182, v182, s0
	ds_write_b16 v72, v182 offset:17408
	v_pk_mul_f32 v[182:183], v[22:23], v[26:27] op_sel_hi:[0,1]
	ds_write_b16 v73, v23
	v_mul_f32_e32 v23, v27, v29
	v_cvt_pk_bf16_f32 v23, v23, s0
	ds_write_b16 v73, v23 offset:17408
	v_add_f32_e32 v23, v186, v192
	v_pk_mul_f32 v[182:183], v[182:183], v[28:29]
	v_exp_f32_e32 v28, v23
	v_perm_b32 v27, v159, v159, v32
	v_exp_f32_e64 v26, -v23
	v_mul_f32_e32 v23, v28, v27
	v_cvt_pk_bf16_f32 v23, v23, s0
	ds_write_b16 v74, v23
	v_add_f32_e32 v23, v187, v192
	v_exp_f32_e32 v28, v23
	v_perm_b32 v185, v162, v162, v32
	v_exp_f32_e64 v27, -v23
	v_mul_f32_e32 v23, v28, v185
	v_perm_b32 v28, v160, v160, v32
	v_mul_f32_e32 v184, v26, v28
	v_cvt_pk_bf16_f32 v23, v23, s0
	v_perm_b32 v29, v163, v163, v1
	v_cvt_pk_bf16_f32 v184, v184, s0
	ds_write_b16 v74, v184 offset:17408
	v_pk_mul_f32 v[184:185], v[22:23], v[26:27] op_sel_hi:[0,1]
	ds_write_b16 v75, v23
	v_mul_f32_e32 v23, v27, v29
	v_cvt_pk_bf16_f32 v23, v23, s0
	ds_write_b16 v75, v23 offset:17408
	v_add_f32_e32 v23, v188, v192
	v_pk_mul_f32 v[184:185], v[184:185], v[28:29]
	v_exp_f32_e32 v28, v23
	v_perm_b32 v27, v165, v165, v32
	v_exp_f32_e64 v26, -v23
	v_mul_f32_e32 v23, v28, v27
	v_cvt_pk_bf16_f32 v23, v23, s0
	ds_write_b16 v76, v23
	v_add_f32_e32 v23, v189, v192
	v_exp_f32_e32 v28, v23
	v_perm_b32 v187, v168, v168, v32
	v_exp_f32_e64 v27, -v23
	v_mul_f32_e32 v23, v28, v187
	v_perm_b32 v28, v166, v166, v32
	v_mul_f32_e32 v186, v26, v28
	v_cvt_pk_bf16_f32 v23, v23, s0
	v_perm_b32 v29, v169, v169, v1
	v_cvt_pk_bf16_f32 v186, v186, s0
	ds_write_b16 v76, v186 offset:17408
	v_pk_mul_f32 v[186:187], v[22:23], v[26:27] op_sel_hi:[0,1]
	ds_write_b16 v77, v23
	v_mul_f32_e32 v23, v27, v29
	v_cvt_pk_bf16_f32 v23, v23, s0
	ds_write_b16 v77, v23 offset:17408
	v_add_f32_e32 v23, v190, v192
	v_exp_f32_e32 v27, v23
	v_perm_b32 v26, v171, v171, v32
	v_pk_mul_f32 v[186:187], v[186:187], v[28:29]
	v_exp_f32_e64 v28, -v23
	v_mul_f32_e32 v23, v27, v26
	v_cvt_pk_bf16_f32 v23, v23, s0
	ds_write_b16 v78, v23
	v_add_f32_e32 v23, v191, v192
	v_exp_f32_e32 v26, v23
	s_waitcnt vmcnt(2)
	v_exp_f32_e64 v29, -v23
	v_perm_b32 v27, v174, v174, v32
	v_perm_b32 v189, v175, v175, v1
	v_perm_b32 v188, v172, v172, v32
	v_mul_f32_e32 v23, v26, v27
	v_mul_f32_e32 v26, v28, v188
	v_cvt_pk_bf16_f32 v23, v23, s0
	v_cvt_pk_bf16_f32 v26, v26, s0
	ds_write_b16 v78, v26 offset:17408
	ds_write_b16 v79, v23
	v_mul_f32_e32 v23, v29, v189
	v_cvt_pk_bf16_f32 v23, v23, s0
	v_pk_mul_f32 v[28:29], v[22:23], v[28:29] op_sel_hi:[0,1]
	v_cvt_pk_bf16_f32 v24, v24, v25
	v_cvt_pk_bf16_f32 v25, v176, v177
	v_cvt_pk_bf16_f32 v26, v178, v179
	v_cvt_pk_bf16_f32 v27, v180, v181
	v_pk_mul_f32 v[28:29], v[28:29], v[188:189]
	ds_write_b16 v79, v23 offset:17408
	v_cvt_pk_bf16_f32 v176, v182, v183
	v_cvt_pk_bf16_f32 v177, v184, v185
	v_cvt_pk_bf16_f32 v178, v186, v187
	v_cvt_pk_bf16_f32 v179, v28, v29
	ds_write_b128 v57, v[24:27] offset:34816
	ds_write_b128 v57, v[176:179] offset:34832
	s_and_saveexec_b64 s[72:73], s[0:1]
	ds_write_b32 v61, v22
	s_or_b64 exec, exec, s[72:73]
	s_cmp_eq_u32 s75, -1
	s_mov_b32 s10, s76
	s_waitcnt vmcnt(1)
	ds_write_b16 v58, v18 offset:53248
	ds_write_b16_d16_hi v58, v18 offset:53392
	ds_write_b16 v58, v19 offset:53536
	ds_write_b16_d16_hi v58, v19 offset:53680
	ds_write_b16 v58, v20 offset:53824
	ds_write_b16_d16_hi v58, v20 offset:53968
	ds_write_b16 v58, v21 offset:54112
	ds_write_b16_d16_hi v59, v21 offset:53248
	s_cbranch_scc1 .LBB0_1325
	s_cmp_gt_u32 s57, 2
	s_mov_b64 s[72:73], -1
	s_cbranch_scc0 .LBB0_1322
	s_and_b64 s[10:11], s[70:71], exec
	s_cselect_b32 s10, s74, s75
	s_add_i32 s10, s10, s65
	s_mov_b64 s[72:73], 0

.LBB0_1324:
	v_readfirstlane_b32 s62, v42
	v_readfirstlane_b32 s63, v43
	s_and_b64 s[72:73], s[70:71], exec
	s_cselect_b32 s31, 0, 0xffffffd0
	s_cselect_b32 s11, 0, 0xffffffc1
	v_subrev_u32_e32 v18, s31, v139
	v_subrev_u32_e32 v19, s11, v141
	v_lshlrev_b32_e32 v18, 13, v18
	v_lshlrev_b32_e32 v19, 13, v19
	v_subrev_u32_e32 v20, s62, v46
	v_subrev_u32_e32 v21, s62, v44
	v_add_u32_e32 v20, v20, v18
	v_add_u32_e32 v21, v21, v18
	v_add_u32_e32 v18, v18, v42
	v_add_u32_e32 v19, v19, v48
	v_subrev_u32_e32 v18, s62, v18
	v_subrev_u32_e32 v19, s62, v19
	s_add_i32 s31, s10, s31
	s_lshl_b32 s31, s31, 13
	s_add_u32 s62, s62, s31
	s_addc_u32 s63, s63, 0
	s_and_b64 s[72:73], s[70:71], exec
	s_mov_b32 s72, 0x2000
	s_cselect_b32 s72, s72, 0xffffe000
	s_cselect_b32 s73, 0, -1
	global_load_dword v115, v20, s[62:63]
	global_load_dword v116, v21, s[62:63]
	global_load_dword v118, v18, s[62:63]
	s_add_u32 s62, s62, s72
	s_addc_u32 s63, s63, s73
	global_load_dword v119, v20, s[62:63]
	global_load_dword v121, v21, s[62:63]
	global_load_dword v122, v18, s[62:63]
	s_add_u32 s62, s62, s72
	s_addc_u32 s63, s63, s73
	global_load_dword v124, v20, s[62:63]
	global_load_dword v127, v21, s[62:63]
	global_load_dword v130, v18, s[62:63]
	s_add_u32 s62, s62, s72
	s_addc_u32 s63, s63, s73
	global_load_dword v132, v20, s[62:63]
	global_load_dword v133, v21, s[62:63]
	global_load_dword v135, v18, s[62:63]
	s_add_u32 s62, s62, s72
	s_addc_u32 s63, s63, s73
	global_load_dword v136, v20, s[62:63]
	global_load_dword v137, v21, s[62:63]
	global_load_dword v138, v18, s[62:63]
	s_add_u32 s62, s62, s72
	s_addc_u32 s63, s63, s73
	global_load_dword v143, v20, s[62:63]
	global_load_dword v144, v21, s[62:63]
	global_load_dword v145, v18, s[62:63]
	s_add_u32 s62, s62, s72
	s_addc_u32 s63, s63, s73
	global_load_dword v146, v20, s[62:63]
	global_load_dword v147, v21, s[62:63]
	global_load_dword v148, v18, s[62:63]
	s_add_u32 s62, s62, s72
	s_addc_u32 s63, s63, s73
	global_load_dword v149, v20, s[62:63]
	global_load_dword v150, v21, s[62:63]
	global_load_dword v151, v18, s[62:63]
	s_add_u32 s62, s62, s72
	s_addc_u32 s63, s63, s73
	global_load_dword v152, v20, s[62:63]
	global_load_dword v153, v21, s[62:63]
	global_load_dword v154, v18, s[62:63]
	s_add_u32 s62, s62, s72
	s_addc_u32 s63, s63, s73
	global_load_dword v155, v20, s[62:63]
	global_load_dword v156, v21, s[62:63]
	global_load_dword v157, v18, s[62:63]
	s_add_u32 s62, s62, s72
	s_addc_u32 s63, s63, s73
	global_load_dword v158, v20, s[62:63]
	global_load_dword v159, v21, s[62:63]
	global_load_dword v160, v18, s[62:63]
	s_add_u32 s62, s62, s72
	s_addc_u32 s63, s63, s73
	global_load_dword v161, v20, s[62:63]
	global_load_dword v162, v21, s[62:63]
	global_load_dword v163, v18, s[62:63]
	s_add_u32 s62, s62, s72
	s_addc_u32 s63, s63, s73
	global_load_dword v164, v20, s[62:63]
	global_load_dword v165, v21, s[62:63]
	global_load_dword v166, v18, s[62:63]
	s_add_u32 s62, s62, s72
	s_addc_u32 s63, s63, s73
	global_load_dword v167, v20, s[62:63]
	global_load_dword v168, v21, s[62:63]
	global_load_dword v169, v18, s[62:63]
	s_add_u32 s62, s62, s72
	s_addc_u32 s63, s63, s73
	global_load_dword v170, v20, s[62:63]
	global_load_dword v171, v21, s[62:63]
	global_load_dword v172, v18, s[62:63]
	s_add_u32 s62, s62, s72
	s_addc_u32 s63, s63, s73
	global_load_dword v173, v20, s[62:63]
	global_load_dword v174, v21, s[62:63]
	global_load_dword v175, v18, s[62:63]
	s_and_b64 s[72:73], s[70:71], exec
	s_cselect_b32 s72, 0xfffe2000, 0
	s_cselect_b32 s73, -1, 0
	s_add_u32 s62, s62, s72
	s_addc_u32 s63, s63, s73
	global_load_dwordx4 v[18:21], v19, s[62:63]
	s_and_b64 s[72:73], s[70:71], exec
	s_cselect_b32 s62, s74, s75
	s_cselect_b32 s63, 64, 0xffffff81
	s_movk_i32 s31, 0x100
	s_cselect_b32 s31, s31, 0xffffe000
	s_movk_i32 s11, 0xc00
	s_cselect_b32 s11, s11, 0x1000
	s_add_i32 s62, s62, s63
	s_add_i32 s31, s31, s56
	s_cmp_gt_u32 s57, 1
	s_cselect_b32 s31, s65, s31
	s_add_i32 s62, s62, s31
	s_ashr_i32 s63, s62, 19
	s_lshl_b32 s62, s62, 13
	s_add_u32 s62, s62, s34
	s_addc_u32 s63, s63, s35
	v_readfirstlane_b32 s72, v207
	s_lshr_b32 s72, s72, 6
	s_lshr_b32 s73, s72, 1
	s_and_b32 s72, s72, 1
	s_lshl_b32 s72, s72, 7
	s_cmp_eq_u32 s73, 1
	s_cselect_b32 s11, 0x1400, s11
	s_cmp_eq_u32 s73, 0
	s_cselect_b32 s11, 0, s11
	s_bfe_u32 s31, s53, 0x20006
	s_lshl_b32 s31, s31, 8
	s_add_i32 s11, s11, s31
	s_add_i32 s11, s11, s72
	s_bfe_u32 s72, s53, 0x20003
	s_lshl_b32 s72, s72, 7
	s_lshl_b32 s31, s31, 1
	s_add_i32 s31, s31, s72
	s_addk_i32 s31, 0x400
	s_cmp_eq_u32 s73, 3
	s_cselect_b32 s11, s31, s11
	s_add_u32 s62, s62, s11
	s_addc_u32 s63, s63, 0
	v_and_b32_e32 v200, 63, v207
	v_lshlrev_b32_e32 v200, 13, v200
	global_load_dword v201, v200, s[62:63]
